# nt (non-temporal) hint on the 16 in-proj epilogue stores
# speedup vs baseline: 1.0067x; 1.0067x over previous
.LBB0_180:
	s_ashr_i32 s29, s28, 31
	s_lshl_b64 s[28:29], s[28:29], 1
	s_add_u32 s28, s30, s28
	s_addc_u32 s29, s31, s29
	v_lshl_add_u64 v[122:123], s[24:25], 0, v[138:139]
	v_lshl_add_u64 v[120:121], s[28:29], 0, v[136:137]
	v_mad_u64_u32 v[124:125], s[28:29], v122, s26, 0
	v_mov_b32_e32 v122, v125
	v_mad_u64_u32 v[122:123], s[28:29], v123, s26, v[122:123]
	v_mov_b32_e32 v125, v122
	v_lshl_add_u64 v[122:123], v[124:125], 1, v[120:121]
	v_cvt_pk_bf16_f32 v124, v166, v167
	v_cvt_pk_bf16_f32 v125, v168, v169
	v_cvt_pk_bf16_f32 v126, v170, v171
	v_cvt_pk_bf16_f32 v127, v172, v173
	s_cmp_gt_i32 s13, 2
	s_mov_b64 s[28:29], -1
	global_store_dwordx4 v[122:123], v[124:127], off nt
	s_cbranch_scc0 .LBB0_182
	s_nop 0
	v_mul_f32_e32 v124, 0xbfb8aa3b, v116
	v_mul_f32_e32 v125, 0xbfb8aa3b, v117
	v_mul_f32_e32 v126, 0xbfb8aa3b, v118
	v_mul_f32_e32 v127, 0xbfb8aa3b, v119
	v_mul_f32_e32 v166, 0xbfb8aa3b, v112
	v_mul_f32_e32 v167, 0xbfb8aa3b, v113
	v_mul_f32_e32 v168, 0xbfb8aa3b, v114
	v_mul_f32_e32 v169, 0xbfb8aa3b, v115
	v_exp_f32_e32 v124, v124
	v_exp_f32_e32 v125, v125
	v_exp_f32_e32 v126, v126
	v_exp_f32_e32 v127, v127
	v_exp_f32_e32 v166, v166
	v_exp_f32_e32 v167, v167
	v_exp_f32_e32 v168, v168
	v_exp_f32_e32 v169, v169
	v_add_f32_e32 v124, 1.0, v124
	v_add_f32_e32 v125, 1.0, v125
	v_add_f32_e32 v126, 1.0, v126
	v_add_f32_e32 v127, 1.0, v127
	v_add_f32_e32 v166, 1.0, v166
	v_add_f32_e32 v167, 1.0, v167
	v_add_f32_e32 v168, 1.0, v168
	v_add_f32_e32 v169, 1.0, v169
	v_rcp_f32_e32 v124, v124
	v_rcp_f32_e32 v125, v125
	v_rcp_f32_e32 v126, v126
	v_rcp_f32_e32 v127, v127
	v_rcp_f32_e32 v166, v166
	v_rcp_f32_e32 v167, v167
	v_rcp_f32_e32 v168, v168
	v_rcp_f32_e32 v169, v169
	s_mov_b64 s[28:29], 0

.LBB0_186:
	v_cvt_pk_bf16_f32 v112, v124, v125
	v_cvt_pk_bf16_f32 v113, v126, v127
	v_cvt_pk_bf16_f32 v114, v166, v167
	v_cvt_pk_bf16_f32 v115, v168, v169
	global_store_dwordx4 v[122:123], v[112:115], off offset:256 nt
	s_cmp_gt_i32 s13, 2
	s_mov_b64 s[28:29], -1
	s_cbranch_scc0 .LBB0_188
	v_mul_f32_e32 v112, 0xbfb8aa3b, v108
	v_exp_f32_e32 v112, v112
	v_mul_f32_e32 v113, 0xbfb8aa3b, v109
	v_exp_f32_e32 v113, v113
	v_mul_f32_e32 v115, 0xbfb8aa3b, v111
	v_add_f32_e32 v112, 1.0, v112
	v_rcp_f32_e32 v114, v112
	v_mul_f32_e32 v112, 0xbfb8aa3b, v110
	v_exp_f32_e32 v112, v112
	v_exp_f32_e32 v117, v115
	v_add_f32_e32 v113, 1.0, v113
	v_rcp_f32_e32 v115, v113
	v_add_f32_e32 v112, 1.0, v112
	v_mul_f32_e32 v113, 0xbfb8aa3b, v104
	v_rcp_f32_e32 v116, v112
	v_add_f32_e32 v112, 1.0, v117
	v_exp_f32_e32 v113, v113
	v_mul_f32_e32 v117, 0xbfb8aa3b, v105
	v_exp_f32_e32 v119, v117
	v_rcp_f32_e32 v117, v112
	v_add_f32_e32 v112, 1.0, v113
	v_mul_f32_e32 v113, 0xbfb8aa3b, v106
	v_rcp_f32_e32 v118, v112
	v_add_f32_e32 v112, 1.0, v119
	v_exp_f32_e32 v113, v113
	v_mul_f32_e32 v119, 0xbfb8aa3b, v107
	v_exp_f32_e32 v123, v119
	v_rcp_f32_e32 v119, v112
	v_add_f32_e32 v112, 1.0, v113
	v_rcp_f32_e32 v122, v112
	v_add_f32_e32 v112, 1.0, v123
	v_rcp_f32_e32 v123, v112
	s_mov_b64 s[28:29], 0

.LBB0_192:
	v_lshl_add_u64 v[104:105], s[24:25], 0, v[142:143]
	v_mad_u64_u32 v[106:107], s[28:29], v104, s26, 0
	v_mov_b32_e32 v104, v107
	v_mad_u64_u32 v[104:105], s[28:29], v105, s26, v[104:105]
	v_mov_b32_e32 v107, v104
	v_lshl_add_u64 v[104:105], v[106:107], 1, v[120:121]
	v_cvt_pk_bf16_f32 v106, v114, v115
	v_cvt_pk_bf16_f32 v107, v116, v117
	v_cvt_pk_bf16_f32 v108, v118, v119
	v_cvt_pk_bf16_f32 v109, v122, v123
	s_cmp_gt_i32 s13, 2
	s_mov_b64 s[28:29], -1
	global_store_dwordx4 v[104:105], v[106:109], off nt
	s_cbranch_scc0 .LBB0_194
	s_nop 0
	v_mul_f32_e32 v106, 0xbfb8aa3b, v100
	v_mul_f32_e32 v107, 0xbfb8aa3b, v101
	v_mul_f32_e32 v108, 0xbfb8aa3b, v102
	v_mul_f32_e32 v109, 0xbfb8aa3b, v103
	v_mul_f32_e32 v110, 0xbfb8aa3b, v96
	v_mul_f32_e32 v111, 0xbfb8aa3b, v97
	v_mul_f32_e32 v114, 0xbfb8aa3b, v98
	v_mul_f32_e32 v115, 0xbfb8aa3b, v99
	v_exp_f32_e32 v106, v106
	v_exp_f32_e32 v107, v107
	v_exp_f32_e32 v108, v108
	v_exp_f32_e32 v109, v109
	v_exp_f32_e32 v110, v110
	v_exp_f32_e32 v111, v111
	v_exp_f32_e32 v114, v114
	v_exp_f32_e32 v115, v115
	v_add_f32_e32 v106, 1.0, v106
	v_add_f32_e32 v107, 1.0, v107
	v_add_f32_e32 v108, 1.0, v108
	v_add_f32_e32 v109, 1.0, v109
	v_add_f32_e32 v110, 1.0, v110
	v_add_f32_e32 v111, 1.0, v111
	v_add_f32_e32 v114, 1.0, v114
	v_add_f32_e32 v115, 1.0, v115
	v_rcp_f32_e32 v106, v106
	v_rcp_f32_e32 v107, v107
	v_rcp_f32_e32 v108, v108
	v_rcp_f32_e32 v109, v109
	v_rcp_f32_e32 v110, v110
	v_rcp_f32_e32 v111, v111
	v_rcp_f32_e32 v114, v114
	v_rcp_f32_e32 v115, v115
	s_mov_b64 s[28:29], 0

.LBB0_198:
	v_cvt_pk_bf16_f32 v96, v106, v107
	v_cvt_pk_bf16_f32 v97, v108, v109
	v_cvt_pk_bf16_f32 v98, v110, v111
	v_cvt_pk_bf16_f32 v99, v114, v115
	global_store_dwordx4 v[104:105], v[96:99], off offset:256 nt
	s_cmp_gt_i32 s13, 2
	s_mov_b64 s[28:29], -1
	s_cbranch_scc0 .LBB0_200
	v_mul_f32_e32 v96, 0xbfb8aa3b, v92
	v_exp_f32_e32 v96, v96
	v_mul_f32_e32 v97, 0xbfb8aa3b, v93
	v_exp_f32_e32 v97, v97
	v_mul_f32_e32 v99, 0xbfb8aa3b, v95
	v_add_f32_e32 v96, 1.0, v96
	v_rcp_f32_e32 v98, v96
	v_mul_f32_e32 v96, 0xbfb8aa3b, v94
	v_exp_f32_e32 v96, v96
	v_exp_f32_e32 v101, v99
	v_add_f32_e32 v97, 1.0, v97
	v_rcp_f32_e32 v99, v97
	v_add_f32_e32 v96, 1.0, v96
	v_mul_f32_e32 v97, 0xbfb8aa3b, v88
	v_rcp_f32_e32 v100, v96
	v_add_f32_e32 v96, 1.0, v101
	v_exp_f32_e32 v97, v97
	v_mul_f32_e32 v101, 0xbfb8aa3b, v89
	v_exp_f32_e32 v103, v101
	v_rcp_f32_e32 v101, v96
	v_add_f32_e32 v96, 1.0, v97
	v_mul_f32_e32 v97, 0xbfb8aa3b, v90
	v_rcp_f32_e32 v102, v96
	v_add_f32_e32 v96, 1.0, v103
	v_exp_f32_e32 v97, v97
	v_mul_f32_e32 v103, 0xbfb8aa3b, v91
	v_exp_f32_e32 v105, v103
	v_rcp_f32_e32 v103, v96
	v_add_f32_e32 v96, 1.0, v97
	v_rcp_f32_e32 v104, v96
	v_add_f32_e32 v96, 1.0, v105
	v_rcp_f32_e32 v105, v96
	s_mov_b64 s[28:29], 0

.LBB0_204:
	v_lshl_add_u64 v[88:89], s[24:25], 0, v[144:145]
	v_mad_u64_u32 v[90:91], s[28:29], v88, s26, 0
	v_mov_b32_e32 v88, v91
	v_mad_u64_u32 v[88:89], s[28:29], v89, s26, v[88:89]
	v_mov_b32_e32 v91, v88
	v_lshl_add_u64 v[88:89], v[90:91], 1, v[120:121]
	v_cvt_pk_bf16_f32 v90, v98, v99
	v_cvt_pk_bf16_f32 v91, v100, v101
	v_cvt_pk_bf16_f32 v92, v102, v103
	v_cvt_pk_bf16_f32 v93, v104, v105
	s_cmp_gt_i32 s13, 2
	s_mov_b64 s[28:29], -1
	global_store_dwordx4 v[88:89], v[90:93], off nt
	s_cbranch_scc0 .LBB0_206
	s_nop 0
	v_mul_f32_e32 v90, 0xbfb8aa3b, v84
	v_mul_f32_e32 v91, 0xbfb8aa3b, v85
	v_mul_f32_e32 v92, 0xbfb8aa3b, v86
	v_mul_f32_e32 v93, 0xbfb8aa3b, v87
	v_mul_f32_e32 v94, 0xbfb8aa3b, v80
	v_mul_f32_e32 v95, 0xbfb8aa3b, v81
	v_mul_f32_e32 v98, 0xbfb8aa3b, v82
	v_mul_f32_e32 v99, 0xbfb8aa3b, v83
	v_exp_f32_e32 v90, v90
	v_exp_f32_e32 v91, v91
	v_exp_f32_e32 v92, v92
	v_exp_f32_e32 v93, v93
	v_exp_f32_e32 v94, v94
	v_exp_f32_e32 v95, v95
	v_exp_f32_e32 v98, v98
	v_exp_f32_e32 v99, v99
	v_add_f32_e32 v90, 1.0, v90
	v_add_f32_e32 v91, 1.0, v91
	v_add_f32_e32 v92, 1.0, v92
	v_add_f32_e32 v93, 1.0, v93
	v_add_f32_e32 v94, 1.0, v94
	v_add_f32_e32 v95, 1.0, v95
	v_add_f32_e32 v98, 1.0, v98
	v_add_f32_e32 v99, 1.0, v99
	v_rcp_f32_e32 v90, v90
	v_rcp_f32_e32 v91, v91
	v_rcp_f32_e32 v92, v92
	v_rcp_f32_e32 v93, v93
	v_rcp_f32_e32 v94, v94
	v_rcp_f32_e32 v95, v95
	v_rcp_f32_e32 v98, v98
	v_rcp_f32_e32 v99, v99
	s_mov_b64 s[28:29], 0

.LBB0_210:
	v_cvt_pk_bf16_f32 v80, v90, v91
	v_cvt_pk_bf16_f32 v81, v92, v93
	v_cvt_pk_bf16_f32 v82, v94, v95
	v_cvt_pk_bf16_f32 v83, v98, v99
	global_store_dwordx4 v[88:89], v[80:83], off offset:256 nt
	s_cmp_gt_i32 s13, 2
	s_mov_b64 s[28:29], -1
	s_cbranch_scc0 .LBB0_212
	v_mul_f32_e32 v80, 0xbfb8aa3b, v76
	v_exp_f32_e32 v80, v80
	v_mul_f32_e32 v81, 0xbfb8aa3b, v77
	v_exp_f32_e32 v81, v81
	v_mul_f32_e32 v83, 0xbfb8aa3b, v79
	v_add_f32_e32 v80, 1.0, v80
	v_rcp_f32_e32 v82, v80
	v_mul_f32_e32 v80, 0xbfb8aa3b, v78
	v_exp_f32_e32 v80, v80
	v_exp_f32_e32 v85, v83
	v_add_f32_e32 v81, 1.0, v81
	v_rcp_f32_e32 v83, v81
	v_add_f32_e32 v80, 1.0, v80
	v_mul_f32_e32 v81, 0xbfb8aa3b, v72
	v_rcp_f32_e32 v84, v80
	v_add_f32_e32 v80, 1.0, v85
	v_exp_f32_e32 v81, v81
	v_mul_f32_e32 v85, 0xbfb8aa3b, v73
	v_exp_f32_e32 v87, v85
	v_rcp_f32_e32 v85, v80
	v_add_f32_e32 v80, 1.0, v81
	v_mul_f32_e32 v81, 0xbfb8aa3b, v74
	v_rcp_f32_e32 v86, v80
	v_add_f32_e32 v80, 1.0, v87
	v_exp_f32_e32 v81, v81
	v_mul_f32_e32 v87, 0xbfb8aa3b, v75
	v_exp_f32_e32 v89, v87
	v_rcp_f32_e32 v87, v80
	v_add_f32_e32 v80, 1.0, v81
	v_rcp_f32_e32 v88, v80
	v_add_f32_e32 v80, 1.0, v89
	v_rcp_f32_e32 v89, v80
	s_mov_b64 s[28:29], 0

.LBB0_216:
	v_lshl_add_u64 v[72:73], s[24:25], 0, v[146:147]
	v_mad_u64_u32 v[74:75], s[28:29], v72, s26, 0
	v_mov_b32_e32 v72, v75
	v_mad_u64_u32 v[72:73], s[28:29], v73, s26, v[72:73]
	v_mov_b32_e32 v75, v72
	v_lshl_add_u64 v[72:73], v[74:75], 1, v[120:121]
	v_cvt_pk_bf16_f32 v74, v82, v83
	v_cvt_pk_bf16_f32 v75, v84, v85
	v_cvt_pk_bf16_f32 v76, v86, v87
	v_cvt_pk_bf16_f32 v77, v88, v89
	s_cmp_gt_i32 s13, 2
	s_mov_b64 s[28:29], -1
	global_store_dwordx4 v[72:73], v[74:77], off nt
	s_cbranch_scc0 .LBB0_218
	s_nop 0
	v_mul_f32_e32 v74, 0xbfb8aa3b, v68
	v_mul_f32_e32 v75, 0xbfb8aa3b, v69
	v_mul_f32_e32 v76, 0xbfb8aa3b, v70
	v_mul_f32_e32 v77, 0xbfb8aa3b, v71
	v_mul_f32_e32 v78, 0xbfb8aa3b, v64
	v_mul_f32_e32 v79, 0xbfb8aa3b, v65
	v_mul_f32_e32 v82, 0xbfb8aa3b, v66
	v_mul_f32_e32 v83, 0xbfb8aa3b, v67
	v_exp_f32_e32 v74, v74
	v_exp_f32_e32 v75, v75
	v_exp_f32_e32 v76, v76
	v_exp_f32_e32 v77, v77
	v_exp_f32_e32 v78, v78
	v_exp_f32_e32 v79, v79
	v_exp_f32_e32 v82, v82
	v_exp_f32_e32 v83, v83
	v_add_f32_e32 v74, 1.0, v74
	v_add_f32_e32 v75, 1.0, v75
	v_add_f32_e32 v76, 1.0, v76
	v_add_f32_e32 v77, 1.0, v77
	v_add_f32_e32 v78, 1.0, v78
	v_add_f32_e32 v79, 1.0, v79
	v_add_f32_e32 v82, 1.0, v82
	v_add_f32_e32 v83, 1.0, v83
	v_rcp_f32_e32 v74, v74
	v_rcp_f32_e32 v75, v75
	v_rcp_f32_e32 v76, v76
	v_rcp_f32_e32 v77, v77
	v_rcp_f32_e32 v78, v78
	v_rcp_f32_e32 v79, v79
	v_rcp_f32_e32 v82, v82
	v_rcp_f32_e32 v83, v83
	s_mov_b64 s[28:29], 0

.LBB0_222:
	v_cvt_pk_bf16_f32 v64, v74, v75
	v_cvt_pk_bf16_f32 v65, v76, v77
	v_cvt_pk_bf16_f32 v66, v78, v79
	v_cvt_pk_bf16_f32 v67, v82, v83
	global_store_dwordx4 v[72:73], v[64:67], off offset:256 nt
	s_cmp_gt_i32 s13, 2
	s_mov_b64 s[28:29], -1
	s_cbranch_scc0 .LBB0_224
	v_mul_f32_e32 v64, 0xbfb8aa3b, v60
	v_exp_f32_e32 v64, v64
	v_mul_f32_e32 v65, 0xbfb8aa3b, v61
	v_exp_f32_e32 v65, v65
	v_mul_f32_e32 v67, 0xbfb8aa3b, v63
	v_add_f32_e32 v64, 1.0, v64
	v_rcp_f32_e32 v66, v64
	v_mul_f32_e32 v64, 0xbfb8aa3b, v62
	v_exp_f32_e32 v64, v64
	v_exp_f32_e32 v69, v67
	v_add_f32_e32 v65, 1.0, v65
	v_rcp_f32_e32 v67, v65
	v_add_f32_e32 v64, 1.0, v64
	v_mul_f32_e32 v65, 0xbfb8aa3b, v56
	v_rcp_f32_e32 v68, v64
	v_add_f32_e32 v64, 1.0, v69
	v_exp_f32_e32 v65, v65
	v_mul_f32_e32 v69, 0xbfb8aa3b, v57
	v_exp_f32_e32 v71, v69
	v_rcp_f32_e32 v69, v64
	v_add_f32_e32 v64, 1.0, v65
	v_mul_f32_e32 v65, 0xbfb8aa3b, v58
	v_rcp_f32_e32 v70, v64
	v_add_f32_e32 v64, 1.0, v71
	v_exp_f32_e32 v65, v65
	v_mul_f32_e32 v71, 0xbfb8aa3b, v59
	v_exp_f32_e32 v73, v71
	v_rcp_f32_e32 v71, v64
	v_add_f32_e32 v64, 1.0, v65
	v_rcp_f32_e32 v72, v64
	v_add_f32_e32 v64, 1.0, v73
	v_rcp_f32_e32 v73, v64
	s_mov_b64 s[28:29], 0

.LBB0_228:
	v_lshl_add_u64 v[56:57], s[24:25], 0, v[148:149]
	v_mad_u64_u32 v[58:59], s[28:29], v56, s26, 0
	v_mov_b32_e32 v56, v59
	v_mad_u64_u32 v[56:57], s[28:29], v57, s26, v[56:57]
	v_mov_b32_e32 v59, v56
	v_lshl_add_u64 v[56:57], v[58:59], 1, v[120:121]
	v_cvt_pk_bf16_f32 v58, v66, v67
	v_cvt_pk_bf16_f32 v59, v68, v69
	v_cvt_pk_bf16_f32 v60, v70, v71
	v_cvt_pk_bf16_f32 v61, v72, v73
	s_cmp_gt_i32 s13, 2
	s_mov_b64 s[28:29], -1
	global_store_dwordx4 v[56:57], v[58:61], off nt
	s_cbranch_scc0 .LBB0_230
	s_nop 0
	v_mul_f32_e32 v58, 0xbfb8aa3b, v52
	v_mul_f32_e32 v59, 0xbfb8aa3b, v53
	v_mul_f32_e32 v60, 0xbfb8aa3b, v54
	v_mul_f32_e32 v61, 0xbfb8aa3b, v55
	v_mul_f32_e32 v62, 0xbfb8aa3b, v48
	v_mul_f32_e32 v63, 0xbfb8aa3b, v49
	v_mul_f32_e32 v66, 0xbfb8aa3b, v50
	v_mul_f32_e32 v67, 0xbfb8aa3b, v51
	v_exp_f32_e32 v58, v58
	v_exp_f32_e32 v59, v59
	v_exp_f32_e32 v60, v60
	v_exp_f32_e32 v61, v61
	v_exp_f32_e32 v62, v62
	v_exp_f32_e32 v63, v63
	v_exp_f32_e32 v66, v66
	v_exp_f32_e32 v67, v67
	v_add_f32_e32 v58, 1.0, v58
	v_add_f32_e32 v59, 1.0, v59
	v_add_f32_e32 v60, 1.0, v60
	v_add_f32_e32 v61, 1.0, v61
	v_add_f32_e32 v62, 1.0, v62
	v_add_f32_e32 v63, 1.0, v63
	v_add_f32_e32 v66, 1.0, v66
	v_add_f32_e32 v67, 1.0, v67
	v_rcp_f32_e32 v58, v58
	v_rcp_f32_e32 v59, v59
	v_rcp_f32_e32 v60, v60
	v_rcp_f32_e32 v61, v61
	v_rcp_f32_e32 v62, v62
	v_rcp_f32_e32 v63, v63
	v_rcp_f32_e32 v66, v66
	v_rcp_f32_e32 v67, v67
	s_mov_b64 s[28:29], 0

.LBB0_234:
	v_cvt_pk_bf16_f32 v48, v58, v59
	v_cvt_pk_bf16_f32 v49, v60, v61
	v_cvt_pk_bf16_f32 v50, v62, v63
	v_cvt_pk_bf16_f32 v51, v66, v67
	global_store_dwordx4 v[56:57], v[48:51], off offset:256 nt
	s_cmp_gt_i32 s13, 2
	s_mov_b64 s[28:29], -1
	s_cbranch_scc0 .LBB0_236
	v_mul_f32_e32 v48, 0xbfb8aa3b, v44
	v_exp_f32_e32 v48, v48
	v_mul_f32_e32 v49, 0xbfb8aa3b, v45
	v_exp_f32_e32 v49, v49
	v_mul_f32_e32 v51, 0xbfb8aa3b, v47
	v_add_f32_e32 v48, 1.0, v48
	v_rcp_f32_e32 v50, v48
	v_mul_f32_e32 v48, 0xbfb8aa3b, v46
	v_exp_f32_e32 v48, v48
	v_exp_f32_e32 v53, v51
	v_add_f32_e32 v49, 1.0, v49
	v_rcp_f32_e32 v51, v49
	v_add_f32_e32 v48, 1.0, v48
	v_mul_f32_e32 v49, 0xbfb8aa3b, v40
	v_rcp_f32_e32 v52, v48
	v_add_f32_e32 v48, 1.0, v53
	v_exp_f32_e32 v49, v49
	v_mul_f32_e32 v53, 0xbfb8aa3b, v41
	v_exp_f32_e32 v55, v53
	v_rcp_f32_e32 v53, v48
	v_add_f32_e32 v48, 1.0, v49
	v_mul_f32_e32 v49, 0xbfb8aa3b, v42
	v_rcp_f32_e32 v54, v48
	v_add_f32_e32 v48, 1.0, v55
	v_exp_f32_e32 v49, v49
	v_mul_f32_e32 v55, 0xbfb8aa3b, v43
	v_exp_f32_e32 v57, v55
	v_rcp_f32_e32 v55, v48
	v_add_f32_e32 v48, 1.0, v49
	v_rcp_f32_e32 v56, v48
	v_add_f32_e32 v48, 1.0, v57
	v_rcp_f32_e32 v57, v48
	s_mov_b64 s[28:29], 0

.LBB0_240:
	v_lshl_add_u64 v[40:41], s[24:25], 0, v[150:151]
	v_mad_u64_u32 v[42:43], s[28:29], v40, s26, 0
	v_mov_b32_e32 v40, v43
	v_mad_u64_u32 v[40:41], s[28:29], v41, s26, v[40:41]
	v_mov_b32_e32 v43, v40
	v_lshl_add_u64 v[40:41], v[42:43], 1, v[120:121]
	v_cvt_pk_bf16_f32 v42, v50, v51
	v_cvt_pk_bf16_f32 v43, v52, v53
	v_cvt_pk_bf16_f32 v44, v54, v55
	v_cvt_pk_bf16_f32 v45, v56, v57
	s_cmp_gt_i32 s13, 2
	s_mov_b64 s[28:29], -1
	global_store_dwordx4 v[40:41], v[42:45], off nt
	s_cbranch_scc0 .LBB0_242
	s_nop 0
	v_mul_f32_e32 v42, 0xbfb8aa3b, v36
	v_mul_f32_e32 v43, 0xbfb8aa3b, v37
	v_mul_f32_e32 v44, 0xbfb8aa3b, v38
	v_mul_f32_e32 v45, 0xbfb8aa3b, v39
	v_mul_f32_e32 v46, 0xbfb8aa3b, v32
	v_mul_f32_e32 v47, 0xbfb8aa3b, v33
	v_mul_f32_e32 v50, 0xbfb8aa3b, v34
	v_mul_f32_e32 v51, 0xbfb8aa3b, v35
	v_exp_f32_e32 v42, v42
	v_exp_f32_e32 v43, v43
	v_exp_f32_e32 v44, v44
	v_exp_f32_e32 v45, v45
	v_exp_f32_e32 v46, v46
	v_exp_f32_e32 v47, v47
	v_exp_f32_e32 v50, v50
	v_exp_f32_e32 v51, v51
	v_add_f32_e32 v42, 1.0, v42
	v_add_f32_e32 v43, 1.0, v43
	v_add_f32_e32 v44, 1.0, v44
	v_add_f32_e32 v45, 1.0, v45
	v_add_f32_e32 v46, 1.0, v46
	v_add_f32_e32 v47, 1.0, v47
	v_add_f32_e32 v50, 1.0, v50
	v_add_f32_e32 v51, 1.0, v51
	v_rcp_f32_e32 v42, v42
	v_rcp_f32_e32 v43, v43
	v_rcp_f32_e32 v44, v44
	v_rcp_f32_e32 v45, v45
	v_rcp_f32_e32 v46, v46
	v_rcp_f32_e32 v47, v47
	v_rcp_f32_e32 v50, v50
	v_rcp_f32_e32 v51, v51
	s_mov_b64 s[28:29], 0

.LBB0_246:
	v_cvt_pk_bf16_f32 v32, v42, v43
	v_cvt_pk_bf16_f32 v33, v44, v45
	v_cvt_pk_bf16_f32 v34, v46, v47
	v_cvt_pk_bf16_f32 v35, v50, v51
	global_store_dwordx4 v[40:41], v[32:35], off offset:256 nt
	s_cmp_gt_i32 s13, 2
	s_mov_b64 s[28:29], -1
	s_cbranch_scc0 .LBB0_248
	v_mul_f32_e32 v32, 0xbfb8aa3b, v28
	v_exp_f32_e32 v32, v32
	v_mul_f32_e32 v33, 0xbfb8aa3b, v29
	v_exp_f32_e32 v33, v33
	v_mul_f32_e32 v35, 0xbfb8aa3b, v31
	v_add_f32_e32 v32, 1.0, v32
	v_rcp_f32_e32 v34, v32
	v_mul_f32_e32 v32, 0xbfb8aa3b, v30
	v_exp_f32_e32 v32, v32
	v_exp_f32_e32 v37, v35
	v_add_f32_e32 v33, 1.0, v33
	v_rcp_f32_e32 v35, v33
	v_add_f32_e32 v32, 1.0, v32
	v_mul_f32_e32 v33, 0xbfb8aa3b, v24
	v_rcp_f32_e32 v36, v32
	v_add_f32_e32 v32, 1.0, v37
	v_exp_f32_e32 v33, v33
	v_mul_f32_e32 v37, 0xbfb8aa3b, v25
	v_exp_f32_e32 v39, v37
	v_rcp_f32_e32 v37, v32
	v_add_f32_e32 v32, 1.0, v33
	v_mul_f32_e32 v33, 0xbfb8aa3b, v26
	v_rcp_f32_e32 v38, v32
	v_add_f32_e32 v32, 1.0, v39
	v_exp_f32_e32 v33, v33
	v_mul_f32_e32 v39, 0xbfb8aa3b, v27
	v_exp_f32_e32 v41, v39
	v_rcp_f32_e32 v39, v32
	v_add_f32_e32 v32, 1.0, v33
	v_rcp_f32_e32 v40, v32
	v_add_f32_e32 v32, 1.0, v41
	v_rcp_f32_e32 v41, v32
	s_mov_b64 s[28:29], 0

.LBB0_252:
	v_lshl_add_u64 v[24:25], s[24:25], 0, v[152:153]
	v_mad_u64_u32 v[26:27], s[28:29], v24, s26, 0
	v_mov_b32_e32 v24, v27
	v_mad_u64_u32 v[24:25], s[28:29], v25, s26, v[24:25]
	v_mov_b32_e32 v27, v24
	v_lshl_add_u64 v[24:25], v[26:27], 1, v[120:121]
	v_cvt_pk_bf16_f32 v26, v34, v35
	v_cvt_pk_bf16_f32 v27, v36, v37
	v_cvt_pk_bf16_f32 v28, v38, v39
	v_cvt_pk_bf16_f32 v29, v40, v41
	s_cmp_gt_i32 s13, 2
	s_mov_b64 s[28:29], -1
	global_store_dwordx4 v[24:25], v[26:29], off nt
	s_cbranch_scc0 .LBB0_254
	s_nop 0
	v_mul_f32_e32 v26, 0xbfb8aa3b, v20
	v_mul_f32_e32 v27, 0xbfb8aa3b, v21
	v_mul_f32_e32 v28, 0xbfb8aa3b, v22
	v_mul_f32_e32 v29, 0xbfb8aa3b, v23
	v_mul_f32_e32 v30, 0xbfb8aa3b, v16
	v_mul_f32_e32 v31, 0xbfb8aa3b, v17
	v_mul_f32_e32 v34, 0xbfb8aa3b, v18
	v_mul_f32_e32 v35, 0xbfb8aa3b, v19
	v_exp_f32_e32 v26, v26
	v_exp_f32_e32 v27, v27
	v_exp_f32_e32 v28, v28
	v_exp_f32_e32 v29, v29
	v_exp_f32_e32 v30, v30
	v_exp_f32_e32 v31, v31
	v_exp_f32_e32 v34, v34
	v_exp_f32_e32 v35, v35
	v_add_f32_e32 v26, 1.0, v26
	v_add_f32_e32 v27, 1.0, v27
	v_add_f32_e32 v28, 1.0, v28
	v_add_f32_e32 v29, 1.0, v29
	v_add_f32_e32 v30, 1.0, v30
	v_add_f32_e32 v31, 1.0, v31
	v_add_f32_e32 v34, 1.0, v34
	v_add_f32_e32 v35, 1.0, v35
	v_rcp_f32_e32 v26, v26
	v_rcp_f32_e32 v27, v27
	v_rcp_f32_e32 v28, v28
	v_rcp_f32_e32 v29, v29
	v_rcp_f32_e32 v30, v30
	v_rcp_f32_e32 v31, v31
	v_rcp_f32_e32 v34, v34
	v_rcp_f32_e32 v35, v35
	s_mov_b64 s[28:29], 0

.LBB0_258:
	v_cvt_pk_bf16_f32 v16, v26, v27
	v_cvt_pk_bf16_f32 v17, v28, v29
	v_cvt_pk_bf16_f32 v18, v30, v31
	v_cvt_pk_bf16_f32 v19, v34, v35
	global_store_dwordx4 v[24:25], v[16:19], off offset:256 nt
	s_cmp_gt_i32 s13, 2
	s_mov_b64 s[28:29], -1
	s_cbranch_scc0 .LBB0_260
	v_mul_f32_e32 v16, 0xbfb8aa3b, v12
	v_exp_f32_e32 v16, v16
	v_mul_f32_e32 v17, 0xbfb8aa3b, v13
	v_exp_f32_e32 v17, v17
	v_mul_f32_e32 v19, 0xbfb8aa3b, v15
	v_add_f32_e32 v16, 1.0, v16
	v_rcp_f32_e32 v18, v16
	v_mul_f32_e32 v16, 0xbfb8aa3b, v14
	v_exp_f32_e32 v16, v16
	v_exp_f32_e32 v21, v19
	v_add_f32_e32 v17, 1.0, v17
	v_rcp_f32_e32 v19, v17
	v_add_f32_e32 v16, 1.0, v16
	v_mul_f32_e32 v17, 0xbfb8aa3b, v8
	v_rcp_f32_e32 v20, v16
	v_add_f32_e32 v16, 1.0, v21
	v_exp_f32_e32 v17, v17
	v_mul_f32_e32 v21, 0xbfb8aa3b, v9
	v_exp_f32_e32 v23, v21
	v_rcp_f32_e32 v21, v16
	v_add_f32_e32 v16, 1.0, v17
	v_mul_f32_e32 v17, 0xbfb8aa3b, v10
	v_rcp_f32_e32 v22, v16
	v_add_f32_e32 v16, 1.0, v23
	v_exp_f32_e32 v17, v17
	v_mul_f32_e32 v23, 0xbfb8aa3b, v11
	v_exp_f32_e32 v25, v23
	v_rcp_f32_e32 v23, v16
	v_add_f32_e32 v16, 1.0, v17
	v_rcp_f32_e32 v24, v16
	v_add_f32_e32 v16, 1.0, v25
	v_rcp_f32_e32 v25, v16
	s_mov_b64 s[28:29], 0

.LBB0_264:
	v_lshl_add_u64 v[8:9], s[24:25], 0, v[154:155]
	v_mad_u64_u32 v[10:11], s[24:25], v8, s26, 0
	v_mov_b32_e32 v8, v11
	v_mad_u64_u32 v[8:9], s[24:25], v9, s26, v[8:9]
	v_mov_b32_e32 v11, v8
	v_lshl_add_u64 v[8:9], v[10:11], 1, v[120:121]
	v_cvt_pk_bf16_f32 v10, v18, v19
	v_cvt_pk_bf16_f32 v11, v20, v21
	v_cvt_pk_bf16_f32 v12, v22, v23
	v_cvt_pk_bf16_f32 v13, v24, v25
	s_cmp_gt_i32 s13, 2
	s_mov_b64 s[24:25], -1
	global_store_dwordx4 v[8:9], v[10:13], off nt
	s_cbranch_scc0 .LBB0_266
	s_nop 0
	v_mul_f32_e32 v10, 0xbfb8aa3b, v4
	v_mul_f32_e32 v11, 0xbfb8aa3b, v5
	v_mul_f32_e32 v12, 0xbfb8aa3b, v6
	v_mul_f32_e32 v13, 0xbfb8aa3b, v7
	v_mul_f32_e32 v14, 0xbfb8aa3b, v0
	v_mul_f32_e32 v15, 0xbfb8aa3b, v1
	v_mul_f32_e32 v18, 0xbfb8aa3b, v2
	v_mul_f32_e32 v19, 0xbfb8aa3b, v3
	v_exp_f32_e32 v10, v10
	v_exp_f32_e32 v11, v11
	v_exp_f32_e32 v12, v12
	v_exp_f32_e32 v13, v13
	v_exp_f32_e32 v14, v14
	v_exp_f32_e32 v15, v15
	v_exp_f32_e32 v18, v18
	v_exp_f32_e32 v19, v19
	v_add_f32_e32 v10, 1.0, v10
	v_add_f32_e32 v11, 1.0, v11
	v_add_f32_e32 v12, 1.0, v12
	v_add_f32_e32 v13, 1.0, v13
	v_add_f32_e32 v14, 1.0, v14
	v_add_f32_e32 v15, 1.0, v15
	v_add_f32_e32 v18, 1.0, v18
	v_add_f32_e32 v19, 1.0, v19
	v_rcp_f32_e32 v10, v10
	v_rcp_f32_e32 v11, v11
	v_rcp_f32_e32 v12, v12
	v_rcp_f32_e32 v13, v13
	v_rcp_f32_e32 v14, v14
	v_rcp_f32_e32 v15, v15
	v_rcp_f32_e32 v18, v18
	v_rcp_f32_e32 v19, v19
	s_mov_b64 s[24:25], 0

.LBB0_270:
	v_cvt_pk_bf16_f32 v0, v10, v11
	v_cvt_pk_bf16_f32 v1, v12, v13
	v_cvt_pk_bf16_f32 v2, v14, v15
	v_cvt_pk_bf16_f32 v3, v18, v19
	global_store_dwordx4 v[8:9], v[0:3], off offset:256 nt
	s_andn2_b64 vcc, exec, s[16:17]
	s_mov_b64 s[16:17], -1
	s_cbranch_vccnz .LBB0_146
	s_andn2_b64 vcc, exec, s[6:7]
	s_cbranch_vccnz .LBB0_145
	s_barrier
	s_branch .LBB0_145
